# K rms-norm moved out of the attention loops into an in-place pass after the in-projection tile loops
# baseline (speedup 1.0000x reference)
; #define PG8_STAGE(bufoff, gbase, voff) do { _Pragma("unroll") for (int _i = 0; _i < 2; ++_i) \
;         __builtin_amdgcn_global_load_lds((const unsigned*)((const char*)(gbase) + (voff)[_i]), (PG8_LAS unsigned*)(lds + (bufoff) + ldsw + _i * 8192), 16, 0, 0); } while (0)
; #define PG8_WAIT_V(n) asm volatile("s_waitcnt vmcnt(" #n ")" ::: "memory")
; #define PG8_BAR __builtin_amdgcn_s_barrier()
; template <class Epi, class Sched, bool ALIGN_EPI = false, bool SP2 = false>
; __device__ __forceinline__ void gemm_phase(PG8_LAS unsigned char* lds, const Gemm g, const Sched& S, const Epi& E) {
;     ...
;     const char* cA = (const char*)g.A + (size_t)cur.pm * tstep; const char* cB = (const char*)g.Bt + (size_t)cur.pn * tstep;
;     S.a_ready(cur);
;     if constexpr (SP2) {
;         PG8_STAGE(PG8_SB(0, 0), cB, voffB); PG8_STAGE(PG8_SB(0, 1), cB + hstep, voffB); PG8_STAGE(PG8_SA(0, 0), cA, voffA); PG8_STAGE(PG8_SA(0, 1), cA + hstep, voffA);
;         if (wr == 1) PG8_BAR;
;         PG8_WAIT_V(2); PG8_BAR;
;         PG8_STAGE(PG8_SB(1, 0), cB + kstep, voffB); PG8_STAGE(PG8_SA(1, 0), cA + kstep, voffA); PG8_STAGE(PG8_SB(1, 1), cB + hstep + kstep, voffB);
;         PG8_WAIT_V(6); PG8_BAR;
;     } else {
;         PG8_STAGE(PG8_SB(0, 0), cB, voffB); PG8_STAGE(PG8_SA(0, 0), cA, voffA); PG8_STAGE(PG8_SB(0, 1), cB + hstep, voffB); PG8_STAGE(PG8_SA(0, 1), cA + hstep, voffA);
;         if (wr == 1) PG8_BAR;
;         PG8_WAIT_V(4); PG8_BAR;
;         PG8_STAGE(PG8_SB(1, 0), cB + kstep, voffB); PG8_STAGE(PG8_SA(1, 0), cA + kstep, voffA); PG8_STAGE(PG8_SB(1, 1), cB + hstep + kstep, voffB);
;         PG8_WAIT_V(6); PG8_BAR;
.LBB0_134:
	s_add_u32 s12, s4, 0x6a00000
	s_addc_u32 s13, s5, 0
	s_lshl_b32 s14, s14, 5
	s_and_b32 s38, s14, 0x60
	s_add_i32 m0, s33, 0x18000
	v_lshl_add_u64 v[8:9], v[8:9], 0, s[96:97]
	s_lshl_b32 s16, s7, 13
	s_lshl_b32 s17, s38, 7
	s_waitcnt vmcnt(2)
	s_barrier
	global_load_lds_dwordx4 v[8:9], off
	v_lshl_add_u64 v[6:7], v[6:7], 0, s[96:97]
	s_add_i32 m0, s33, 0x1a000
	s_add_i32 s39, s33, 0x8000
	s_add_i32 s40, s33, 0xa000
	global_load_lds_dwordx4 v[6:7], off
	v_lshl_add_u64 v[2:3], v[2:3], 0, s[96:97]
	s_mov_b32 m0, s39
	s_add_u32 s14, s0, 0x40080
	global_load_lds_dwordx4 v[2:3], off
	v_lshl_add_u64 v[2:3], v[4:5], 0, s[96:97]
	s_mov_b32 m0, s40
	s_addc_u32 s15, s1, 0
	global_load_lds_dwordx4 v[2:3], off
	s_add_i32 m0, s33, 0x1c000
	v_lshl_add_u64 v[2:3], s[14:15], 0, v[134:135]
	global_load_lds_dwordx4 v[2:3], off
	v_lshl_add_u64 v[2:3], s[14:15], 0, v[130:131]
	s_add_i32 m0, s33, 0x1e000
	s_cmpk_lt_u32 s6, 0x100
	global_load_lds_dwordx4 v[2:3], off
	v_bfe_u32 v2, v0, 4, 2
	v_and_b32_e32 v3, 15, v0
	v_lshlrev_b32_e32 v138, 3, v2
	v_lshlrev_b32_e32 v2, 4, v2
	v_lshlrev_b32_e32 v0, 2, v0
	v_lshl_or_b32 v139, s7, 6, v3
	v_lshl_or_b32 v3, v3, 6, v2
	v_and_b32_e32 v0, 32, v0
	v_bitop3_b32 v6, v3, s16, v0 bitop3:0xde
	v_bitop3_b32 v163, v3, s17, v0 bitop3:0xde
	v_or_b32_e32 v0, s38, v138
	v_cmp_gt_u32_e64 s[6:7], s72, v0
	v_lshlrev_b32_e32 v0, 2, v0
	v_lshl_add_u64 v[4:5], s[4:5], 0, v[0:1]
	v_mov_b32_e32 v3, v1
	v_lshlrev_b32_e32 v0, 14, v10
	v_lshl_add_u64 v[2:3], s[4:5], 0, v[2:3]
	s_mov_b64 s[4:5], 0x1b800000
	v_and_b32_e32 v0, 0xffff8000, v0
	v_lshl_add_u64 v[142:143], v[2:3], 0, s[4:5]
	v_lshl_add_u32 v0, v11, 11, v0
	v_and_b32_e32 v2, 1, v10
	v_lshl_or_b32 v0, v2, 6, v0
	v_lshl_add_u32 v144, v12, 1, v0
	v_lshlrev_b32_e32 v0, 14, v14
	v_and_b32_e32 v0, 0xffff8000, v0
	s_waitcnt vmcnt(6)
	v_lshl_add_u32 v0, v13, 11, v0
	v_and_b32_e32 v2, 1, v14
	s_mov_b64 s[16:17], 0x16e00000
	v_lshl_or_b32 v0, v2, 6, v0
	v_readlane_b32 s4, v254, 7
	s_cselect_b64 s[14:15], -1, 0
	s_waitcnt lgkmcnt(0)
	s_ashr_i32 s41, s37, 31
	v_lshl_add_u64 v[140:141], v[4:5], 0, s[16:17]
	v_mov_b32_e32 v145, v1
	v_lshl_add_u32 v146, v15, 1, v0
	v_mov_b32_e32 v147, v1
	s_mov_b32 s42, 0
	v_add_u32_e32 v166, 0, v6
	v_readlane_b32 s43, v253, 62
	s_mov_b32 s44, s4
	s_barrier
	v_readlane_b32 s5, v254, 8
	s_mov_b64 s[100:101], 0
	s_branch .LBB0_137

; template <class Epi, class Sched, bool ALIGN_EPI = false, bool SP2 = false>
; __device__ __forceinline__ void gemm_phase(PG8_LAS unsigned char* lds, const Gemm g, const Sched& S, const Epi& E) {
;     ...
;     for (;;) {
;         const bool has_next = S.next(ui + 1, nxt);
;         const char* nA = has_next ? (const char*)g.A + (size_t)nxt.pm * tstep : cA; const char* nB = has_next ? (const char*)g.Bt + (size_t)nxt.pn * tstep : cB;
;         for (int t = 0; t < nt; t += 2) {
;             const bool last = (t == nt - 2);
;             const char* a1 = cA + (size_t)(t + 1) * kstep;
;             const char* a2 = last ? nA : cA + (size_t)(t + 2) * kstep; const char* b2 = last ? nB : cB + (size_t)(t + 2) * kstep;
;             const char* a3 = a2 + kstep; const char* b3 = b2 + kstep;
;             if (last && has_next) S.a_ready(nxt);
.LBB0_143:
	s_and_b32 vcc_lo, s43, -2
	s_cmp_eq_u32 vcc_lo, 2
	s_cbranch_scc0 .Lkn_norec_a
	s_lshl_b64 s[100:101], s[100:101], 10
	s_or_b32 s100, s100, 0x200
	s_and_b32 vcc_lo, s43, 1
	s_lshl_b32 vcc_lo, vcc_lo, 8
	s_or_b32 s100, s100, vcc_lo
	s_or_b32 s100, s100, s44

; #define PG8_WAIT_V(n) asm volatile("s_waitcnt vmcnt(" #n ")" ::: "memory")
; #define PG8_BAR __builtin_amdgcn_s_barrier()
; template <class Epi, class Sched, bool ALIGN_EPI = false, bool SP2 = false>
; __device__ __forceinline__ void gemm_phase(PG8_LAS unsigned char* lds, const Gemm g, const Sched& S, const Epi& E) {
;     ...
;     PG8_WAIT_V(0);
;     if constexpr (!ALIGN_EPI) { if (wr == 0) PG8_BAR; }
;     PG8_BAR;
.LBB0_194:
	s_waitcnt vmcnt(0)
	s_mov_b32 s37, 0x7f800000
	s_movk_i32 s38, 0x5ff
	s_mov_b32 s40, 0xbfb8aa3b
	s_barrier
	v_writelane_b32 v128, s2, 0
	v_writelane_b32 v128, s3, 1
	v_writelane_b32 v128, s4, 2
	v_writelane_b32 v128, s5, 3
	v_writelane_b32 v128, s6, 4
	v_writelane_b32 v128, s7, 5
	v_writelane_b32 v128, s8, 6
	v_writelane_b32 v128, s9, 7
	v_writelane_b32 v128, s10, 8
	v_writelane_b32 v128, s11, 9
	v_readlane_b32 s10, v253, 2
	v_readlane_b32 s11, v253, 3
	s_add_u32 s10, s10, 0x6a00000
	s_addc_u32 s11, s11, 0
	v_and_b32_e32 v2, 7, v210
	v_bfe_u32 v3, v210, 3, 2
	v_lshrrev_b32_e32 v4, 5, v210
	v_mul_u32_u24_e32 v4, 0x2080, v4
	v_lshl_add_u32 v4, v3, 7, v4
	v_lshl_add_u32 v4, v2, 4, v4
.Lkn_a_next:
	s_bitcmp1_b32 s100, 9
	s_cbranch_scc0 .Lkn_a_done
	s_and_b32 s2, s100, 0x7f
	s_bfe_u32 s3, s100, 0x10008
	s_lshr_b64 s[100:101], s[100:101], 10
	s_mul_i32 s4, s2, 0x208000
	s_lshl_b32 s3, s3, 9
	s_add_i32 s3, s3, 0x400
	s_add_u32 s4, s4, s3
	s_add_u32 s6, s10, s4
	s_addc_u32 s7, s11, 0
	s_mov_b32 s5, 0
.Lkn_a_half:
	s_mov_b64 s[8:9], s[6:7]
	global_load_dwordx4 v[8:11], v4, s[6:7]
	s_add_u32 s6, s6, 0x20800
	s_addc_u32 s7, s7, 0
	global_load_dwordx4 v[12:15], v4, s[6:7]
	s_add_u32 s6, s6, 0x20800
	s_addc_u32 s7, s7, 0
	global_load_dwordx4 v[16:19], v4, s[6:7]
	s_add_u32 s6, s6, 0x20800
	s_addc_u32 s7, s7, 0
	global_load_dwordx4 v[20:23], v4, s[6:7]
	s_add_u32 s6, s6, 0x20800
	s_addc_u32 s7, s7, 0
	global_load_dwordx4 v[24:27], v4, s[6:7]
	s_add_u32 s6, s6, 0x20800
	s_addc_u32 s7, s7, 0
	global_load_dwordx4 v[28:31], v4, s[6:7]
	s_add_u32 s6, s6, 0x20800
	s_addc_u32 s7, s7, 0
	global_load_dwordx4 v[32:35], v4, s[6:7]
	s_add_u32 s6, s6, 0x20800
	s_addc_u32 s7, s7, 0
	global_load_dwordx4 v[36:39], v4, s[6:7]
	s_add_u32 s6, s6, 0x20800
	s_addc_u32 s7, s7, 0
	s_waitcnt vmcnt(7)
	v_and_b32_e32 v40, 0xffff0000, v11
	v_lshlrev_b32_e32 v44, 16, v11
	v_mul_f32_e32 v40, v40, v40
	v_fmac_f32_e32 v40, v44, v44
	v_and_b32_e32 v41, 0xffff0000, v10
	v_lshlrev_b32_e32 v44, 16, v10
	v_mul_f32_e32 v41, v41, v41
	v_fmac_f32_e32 v41, v44, v44
	v_and_b32_e32 v42, 0xffff0000, v8
	v_lshlrev_b32_e32 v44, 16, v8
	v_mul_f32_e32 v42, v42, v42
	v_fmac_f32_e32 v42, v44, v44
	v_and_b32_e32 v43, 0xffff0000, v9
	v_lshlrev_b32_e32 v44, 16, v9
	v_mul_f32_e32 v43, v43, v43
	v_fmac_f32_e32 v43, v44, v44
	v_add_f32_e32 v42, v42, v43
	v_add_f32_e32 v41, v41, v42
	v_add_f32_e32 v40, v40, v41
	s_nop 1
	v_add_f32_dpp v40, v40, v40 quad_perm:[1,0,3,2] row_mask:0xf bank_mask:0xf bound_ctrl:1
	s_nop 1
	v_add_f32_dpp v40, v40, v40 quad_perm:[2,3,0,1] row_mask:0xf bank_mask:0xf bound_ctrl:1
	s_nop 1
	v_add_f32_dpp v40, v40, v40 row_half_mirror row_mask:0xf bank_mask:0xf bound_ctrl:1
	v_fmamk_f32 v40, v40, 0x3c800000, v211
	v_rsq_f32_e32 v40, v40
	v_lshlrev_b32_e32 v41, 16, v8
	v_and_b32_e32 v42, 0xffff0000, v8
	v_mul_f32_e32 v41, v40, v41
	v_mul_f32_e32 v42, v40, v42
	v_cvt_pk_bf16_f32 v8, v41, v42
	v_lshlrev_b32_e32 v41, 16, v9
	v_and_b32_e32 v42, 0xffff0000, v9
	v_mul_f32_e32 v41, v40, v41
	v_mul_f32_e32 v42, v40, v42
	v_cvt_pk_bf16_f32 v9, v41, v42
	v_lshlrev_b32_e32 v41, 16, v10
	v_and_b32_e32 v42, 0xffff0000, v10
	v_mul_f32_e32 v41, v40, v41
	v_mul_f32_e32 v42, v40, v42
	v_cvt_pk_bf16_f32 v10, v41, v42
	v_lshlrev_b32_e32 v41, 16, v11
	v_and_b32_e32 v42, 0xffff0000, v11
	v_mul_f32_e32 v41, v40, v41
	v_mul_f32_e32 v42, v40, v42
	v_cvt_pk_bf16_f32 v11, v41, v42
	global_store_dwordx4 v4, v[8:11], s[8:9]
	s_add_u32 s8, s8, 0x20800
	s_addc_u32 s9, s9, 0
	s_waitcnt vmcnt(7)
	v_and_b32_e32 v40, 0xffff0000, v15
	v_lshlrev_b32_e32 v44, 16, v15
	v_mul_f32_e32 v40, v40, v40
	v_fmac_f32_e32 v40, v44, v44
	v_and_b32_e32 v41, 0xffff0000, v14
	v_lshlrev_b32_e32 v44, 16, v14
	v_mul_f32_e32 v41, v41, v41
	v_fmac_f32_e32 v41, v44, v44
	v_and_b32_e32 v42, 0xffff0000, v12
	v_lshlrev_b32_e32 v44, 16, v12
	v_mul_f32_e32 v42, v42, v42
	v_fmac_f32_e32 v42, v44, v44
	v_and_b32_e32 v43, 0xffff0000, v13
	v_lshlrev_b32_e32 v44, 16, v13
	v_mul_f32_e32 v43, v43, v43
	v_fmac_f32_e32 v43, v44, v44
	v_add_f32_e32 v42, v42, v43
	v_add_f32_e32 v41, v41, v42
	v_add_f32_e32 v40, v40, v41
	s_nop 1
	v_add_f32_dpp v40, v40, v40 quad_perm:[1,0,3,2] row_mask:0xf bank_mask:0xf bound_ctrl:1
	s_nop 1
	v_add_f32_dpp v40, v40, v40 quad_perm:[2,3,0,1] row_mask:0xf bank_mask:0xf bound_ctrl:1
	s_nop 1
	v_add_f32_dpp v40, v40, v40 row_half_mirror row_mask:0xf bank_mask:0xf bound_ctrl:1
	v_fmamk_f32 v40, v40, 0x3c800000, v211
	v_rsq_f32_e32 v40, v40
	v_lshlrev_b32_e32 v41, 16, v12
	v_and_b32_e32 v42, 0xffff0000, v12
	v_mul_f32_e32 v41, v40, v41
	v_mul_f32_e32 v42, v40, v42
	v_cvt_pk_bf16_f32 v12, v41, v42
	v_lshlrev_b32_e32 v41, 16, v13
	v_and_b32_e32 v42, 0xffff0000, v13
	v_mul_f32_e32 v41, v40, v41
	v_mul_f32_e32 v42, v40, v42
	v_cvt_pk_bf16_f32 v13, v41, v42
	v_lshlrev_b32_e32 v41, 16, v14
	v_and_b32_e32 v42, 0xffff0000, v14
	v_mul_f32_e32 v41, v40, v41
	v_mul_f32_e32 v42, v40, v42
	v_cvt_pk_bf16_f32 v14, v41, v42
	v_lshlrev_b32_e32 v41, 16, v15
	v_and_b32_e32 v42, 0xffff0000, v15
	v_mul_f32_e32 v41, v40, v41
	v_mul_f32_e32 v42, v40, v42
	v_cvt_pk_bf16_f32 v15, v41, v42
	global_store_dwordx4 v4, v[12:15], s[8:9]
	s_add_u32 s8, s8, 0x20800
	s_addc_u32 s9, s9, 0
	s_waitcnt vmcnt(7)
	v_and_b32_e32 v40, 0xffff0000, v19
	v_lshlrev_b32_e32 v44, 16, v19
	v_mul_f32_e32 v40, v40, v40
	v_fmac_f32_e32 v40, v44, v44
	v_and_b32_e32 v41, 0xffff0000, v18
	v_lshlrev_b32_e32 v44, 16, v18
	v_mul_f32_e32 v41, v41, v41
	v_fmac_f32_e32 v41, v44, v44
	v_and_b32_e32 v42, 0xffff0000, v16
	v_lshlrev_b32_e32 v44, 16, v16
	v_mul_f32_e32 v42, v42, v42
	v_fmac_f32_e32 v42, v44, v44
	v_and_b32_e32 v43, 0xffff0000, v17
	v_lshlrev_b32_e32 v44, 16, v17
	v_mul_f32_e32 v43, v43, v43
	v_fmac_f32_e32 v43, v44, v44
	v_add_f32_e32 v42, v42, v43
	v_add_f32_e32 v41, v41, v42
	v_add_f32_e32 v40, v40, v41
	s_nop 1
	v_add_f32_dpp v40, v40, v40 quad_perm:[1,0,3,2] row_mask:0xf bank_mask:0xf bound_ctrl:1
	s_nop 1
	v_add_f32_dpp v40, v40, v40 quad_perm:[2,3,0,1] row_mask:0xf bank_mask:0xf bound_ctrl:1
	s_nop 1
	v_add_f32_dpp v40, v40, v40 row_half_mirror row_mask:0xf bank_mask:0xf bound_ctrl:1
	v_fmamk_f32 v40, v40, 0x3c800000, v211
	v_rsq_f32_e32 v40, v40
	v_lshlrev_b32_e32 v41, 16, v16
	v_and_b32_e32 v42, 0xffff0000, v16
	v_mul_f32_e32 v41, v40, v41
	v_mul_f32_e32 v42, v40, v42
	v_cvt_pk_bf16_f32 v16, v41, v42
	v_lshlrev_b32_e32 v41, 16, v17
	v_and_b32_e32 v42, 0xffff0000, v17
	v_mul_f32_e32 v41, v40, v41
	v_mul_f32_e32 v42, v40, v42
	v_cvt_pk_bf16_f32 v17, v41, v42
	v_lshlrev_b32_e32 v41, 16, v18
	v_and_b32_e32 v42, 0xffff0000, v18
	v_mul_f32_e32 v41, v40, v41
	v_mul_f32_e32 v42, v40, v42
	v_cvt_pk_bf16_f32 v18, v41, v42
	v_lshlrev_b32_e32 v41, 16, v19
	v_and_b32_e32 v42, 0xffff0000, v19
	v_mul_f32_e32 v41, v40, v41
	v_mul_f32_e32 v42, v40, v42
	v_cvt_pk_bf16_f32 v19, v41, v42
	global_store_dwordx4 v4, v[16:19], s[8:9]
	s_add_u32 s8, s8, 0x20800
	s_addc_u32 s9, s9, 0
	s_waitcnt vmcnt(7)
	v_and_b32_e32 v40, 0xffff0000, v23
	v_lshlrev_b32_e32 v44, 16, v23
	v_mul_f32_e32 v40, v40, v40
	v_fmac_f32_e32 v40, v44, v44
	v_and_b32_e32 v41, 0xffff0000, v22
	v_lshlrev_b32_e32 v44, 16, v22
	v_mul_f32_e32 v41, v41, v41
	v_fmac_f32_e32 v41, v44, v44
	v_and_b32_e32 v42, 0xffff0000, v20
	v_lshlrev_b32_e32 v44, 16, v20
	v_mul_f32_e32 v42, v42, v42
	v_fmac_f32_e32 v42, v44, v44
	v_and_b32_e32 v43, 0xffff0000, v21
	v_lshlrev_b32_e32 v44, 16, v21
	v_mul_f32_e32 v43, v43, v43
	v_fmac_f32_e32 v43, v44, v44
	v_add_f32_e32 v42, v42, v43
	v_add_f32_e32 v41, v41, v42
	v_add_f32_e32 v40, v40, v41
	s_nop 1
	v_add_f32_dpp v40, v40, v40 quad_perm:[1,0,3,2] row_mask:0xf bank_mask:0xf bound_ctrl:1
	s_nop 1
	v_add_f32_dpp v40, v40, v40 quad_perm:[2,3,0,1] row_mask:0xf bank_mask:0xf bound_ctrl:1
	s_nop 1
	v_add_f32_dpp v40, v40, v40 row_half_mirror row_mask:0xf bank_mask:0xf bound_ctrl:1
	v_fmamk_f32 v40, v40, 0x3c800000, v211
	v_rsq_f32_e32 v40, v40
	v_lshlrev_b32_e32 v41, 16, v20
	v_and_b32_e32 v42, 0xffff0000, v20
	v_mul_f32_e32 v41, v40, v41
	v_mul_f32_e32 v42, v40, v42
	v_cvt_pk_bf16_f32 v20, v41, v42
	v_lshlrev_b32_e32 v41, 16, v21
	v_and_b32_e32 v42, 0xffff0000, v21
	v_mul_f32_e32 v41, v40, v41
	v_mul_f32_e32 v42, v40, v42
	v_cvt_pk_bf16_f32 v21, v41, v42
	v_lshlrev_b32_e32 v41, 16, v22
	v_and_b32_e32 v42, 0xffff0000, v22
	v_mul_f32_e32 v41, v40, v41
	v_mul_f32_e32 v42, v40, v42
	v_cvt_pk_bf16_f32 v22, v41, v42
	v_lshlrev_b32_e32 v41, 16, v23
	v_and_b32_e32 v42, 0xffff0000, v23
	v_mul_f32_e32 v41, v40, v41
	v_mul_f32_e32 v42, v40, v42
	v_cvt_pk_bf16_f32 v23, v41, v42
	global_store_dwordx4 v4, v[20:23], s[8:9]
	s_add_u32 s8, s8, 0x20800
	s_addc_u32 s9, s9, 0
	s_waitcnt vmcnt(7)
	v_and_b32_e32 v40, 0xffff0000, v27
	v_lshlrev_b32_e32 v44, 16, v27
	v_mul_f32_e32 v40, v40, v40
	v_fmac_f32_e32 v40, v44, v44
	v_and_b32_e32 v41, 0xffff0000, v26
	v_lshlrev_b32_e32 v44, 16, v26
	v_mul_f32_e32 v41, v41, v41
	v_fmac_f32_e32 v41, v44, v44
	v_and_b32_e32 v42, 0xffff0000, v24
	v_lshlrev_b32_e32 v44, 16, v24
	v_mul_f32_e32 v42, v42, v42
	v_fmac_f32_e32 v42, v44, v44
	v_and_b32_e32 v43, 0xffff0000, v25
	v_lshlrev_b32_e32 v44, 16, v25
	v_mul_f32_e32 v43, v43, v43
	v_fmac_f32_e32 v43, v44, v44
	v_add_f32_e32 v42, v42, v43
	v_add_f32_e32 v41, v41, v42
	v_add_f32_e32 v40, v40, v41
	s_nop 1
	v_add_f32_dpp v40, v40, v40 quad_perm:[1,0,3,2] row_mask:0xf bank_mask:0xf bound_ctrl:1
	s_nop 1
	v_add_f32_dpp v40, v40, v40 quad_perm:[2,3,0,1] row_mask:0xf bank_mask:0xf bound_ctrl:1
	s_nop 1
	v_add_f32_dpp v40, v40, v40 row_half_mirror row_mask:0xf bank_mask:0xf bound_ctrl:1
	v_fmamk_f32 v40, v40, 0x3c800000, v211
	v_rsq_f32_e32 v40, v40
	v_lshlrev_b32_e32 v41, 16, v24
	v_and_b32_e32 v42, 0xffff0000, v24
	v_mul_f32_e32 v41, v40, v41
	v_mul_f32_e32 v42, v40, v42
	v_cvt_pk_bf16_f32 v24, v41, v42
	v_lshlrev_b32_e32 v41, 16, v25
	v_and_b32_e32 v42, 0xffff0000, v25
	v_mul_f32_e32 v41, v40, v41
	v_mul_f32_e32 v42, v40, v42
	v_cvt_pk_bf16_f32 v25, v41, v42
	v_lshlrev_b32_e32 v41, 16, v26
	v_and_b32_e32 v42, 0xffff0000, v26
	v_mul_f32_e32 v41, v40, v41
	v_mul_f32_e32 v42, v40, v42
	v_cvt_pk_bf16_f32 v26, v41, v42
	v_lshlrev_b32_e32 v41, 16, v27
	v_and_b32_e32 v42, 0xffff0000, v27
	v_mul_f32_e32 v41, v40, v41
	v_mul_f32_e32 v42, v40, v42
	v_cvt_pk_bf16_f32 v27, v41, v42
	global_store_dwordx4 v4, v[24:27], s[8:9]
	s_add_u32 s8, s8, 0x20800
	s_addc_u32 s9, s9, 0
	s_waitcnt vmcnt(7)
	v_and_b32_e32 v40, 0xffff0000, v31
	v_lshlrev_b32_e32 v44, 16, v31
	v_mul_f32_e32 v40, v40, v40
	v_fmac_f32_e32 v40, v44, v44
	v_and_b32_e32 v41, 0xffff0000, v30
	v_lshlrev_b32_e32 v44, 16, v30
	v_mul_f32_e32 v41, v41, v41
	v_fmac_f32_e32 v41, v44, v44
	v_and_b32_e32 v42, 0xffff0000, v28
	v_lshlrev_b32_e32 v44, 16, v28
	v_mul_f32_e32 v42, v42, v42
	v_fmac_f32_e32 v42, v44, v44
	v_and_b32_e32 v43, 0xffff0000, v29
	v_lshlrev_b32_e32 v44, 16, v29
	v_mul_f32_e32 v43, v43, v43
	v_fmac_f32_e32 v43, v44, v44
	v_add_f32_e32 v42, v42, v43
	v_add_f32_e32 v41, v41, v42
	v_add_f32_e32 v40, v40, v41
	s_nop 1
	v_add_f32_dpp v40, v40, v40 quad_perm:[1,0,3,2] row_mask:0xf bank_mask:0xf bound_ctrl:1
	s_nop 1
	v_add_f32_dpp v40, v40, v40 quad_perm:[2,3,0,1] row_mask:0xf bank_mask:0xf bound_ctrl:1
	s_nop 1
	v_add_f32_dpp v40, v40, v40 row_half_mirror row_mask:0xf bank_mask:0xf bound_ctrl:1
	v_fmamk_f32 v40, v40, 0x3c800000, v211
	v_rsq_f32_e32 v40, v40
	v_lshlrev_b32_e32 v41, 16, v28
	v_and_b32_e32 v42, 0xffff0000, v28
	v_mul_f32_e32 v41, v40, v41
	v_mul_f32_e32 v42, v40, v42
	v_cvt_pk_bf16_f32 v28, v41, v42
	v_lshlrev_b32_e32 v41, 16, v29
	v_and_b32_e32 v42, 0xffff0000, v29
	v_mul_f32_e32 v41, v40, v41
	v_mul_f32_e32 v42, v40, v42
	v_cvt_pk_bf16_f32 v29, v41, v42
	v_lshlrev_b32_e32 v41, 16, v30
	v_and_b32_e32 v42, 0xffff0000, v30
	v_mul_f32_e32 v41, v40, v41
	v_mul_f32_e32 v42, v40, v42
	v_cvt_pk_bf16_f32 v30, v41, v42
	v_lshlrev_b32_e32 v41, 16, v31
	v_and_b32_e32 v42, 0xffff0000, v31
	v_mul_f32_e32 v41, v40, v41
	v_mul_f32_e32 v42, v40, v42
	v_cvt_pk_bf16_f32 v31, v41, v42
	global_store_dwordx4 v4, v[28:31], s[8:9]
	s_add_u32 s8, s8, 0x20800
	s_addc_u32 s9, s9, 0
	s_waitcnt vmcnt(7)
	v_and_b32_e32 v40, 0xffff0000, v35
	v_lshlrev_b32_e32 v44, 16, v35
	v_mul_f32_e32 v40, v40, v40
	v_fmac_f32_e32 v40, v44, v44
	v_and_b32_e32 v41, 0xffff0000, v34
	v_lshlrev_b32_e32 v44, 16, v34
	v_mul_f32_e32 v41, v41, v41
	v_fmac_f32_e32 v41, v44, v44
	v_and_b32_e32 v42, 0xffff0000, v32
	v_lshlrev_b32_e32 v44, 16, v32
	v_mul_f32_e32 v42, v42, v42
	v_fmac_f32_e32 v42, v44, v44
	v_and_b32_e32 v43, 0xffff0000, v33
	v_lshlrev_b32_e32 v44, 16, v33
	v_mul_f32_e32 v43, v43, v43
	v_fmac_f32_e32 v43, v44, v44
	v_add_f32_e32 v42, v42, v43
	v_add_f32_e32 v41, v41, v42
	v_add_f32_e32 v40, v40, v41
	s_nop 1
	v_add_f32_dpp v40, v40, v40 quad_perm:[1,0,3,2] row_mask:0xf bank_mask:0xf bound_ctrl:1
	s_nop 1
	v_add_f32_dpp v40, v40, v40 quad_perm:[2,3,0,1] row_mask:0xf bank_mask:0xf bound_ctrl:1
	s_nop 1
	v_add_f32_dpp v40, v40, v40 row_half_mirror row_mask:0xf bank_mask:0xf bound_ctrl:1
	v_fmamk_f32 v40, v40, 0x3c800000, v211
	v_rsq_f32_e32 v40, v40
	v_lshlrev_b32_e32 v41, 16, v32
	v_and_b32_e32 v42, 0xffff0000, v32
	v_mul_f32_e32 v41, v40, v41
	v_mul_f32_e32 v42, v40, v42
	v_cvt_pk_bf16_f32 v32, v41, v42
	v_lshlrev_b32_e32 v41, 16, v33
	v_and_b32_e32 v42, 0xffff0000, v33
	v_mul_f32_e32 v41, v40, v41
	v_mul_f32_e32 v42, v40, v42
	v_cvt_pk_bf16_f32 v33, v41, v42
	v_lshlrev_b32_e32 v41, 16, v34
	v_and_b32_e32 v42, 0xffff0000, v34
	v_mul_f32_e32 v41, v40, v41
	v_mul_f32_e32 v42, v40, v42
	v_cvt_pk_bf16_f32 v34, v41, v42
	v_lshlrev_b32_e32 v41, 16, v35
	v_and_b32_e32 v42, 0xffff0000, v35
	v_mul_f32_e32 v41, v40, v41
	v_mul_f32_e32 v42, v40, v42
	v_cvt_pk_bf16_f32 v35, v41, v42
	global_store_dwordx4 v4, v[32:35], s[8:9]
	s_add_u32 s8, s8, 0x20800
	s_addc_u32 s9, s9, 0
	s_waitcnt vmcnt(7)
	v_and_b32_e32 v40, 0xffff0000, v39
	v_lshlrev_b32_e32 v44, 16, v39
	v_mul_f32_e32 v40, v40, v40
	v_fmac_f32_e32 v40, v44, v44
	v_and_b32_e32 v41, 0xffff0000, v38
	v_lshlrev_b32_e32 v44, 16, v38
	v_mul_f32_e32 v41, v41, v41
	v_fmac_f32_e32 v41, v44, v44
	v_and_b32_e32 v42, 0xffff0000, v36
	v_lshlrev_b32_e32 v44, 16, v36
	v_mul_f32_e32 v42, v42, v42
	v_fmac_f32_e32 v42, v44, v44
	v_and_b32_e32 v43, 0xffff0000, v37
	v_lshlrev_b32_e32 v44, 16, v37
	v_mul_f32_e32 v43, v43, v43
	v_fmac_f32_e32 v43, v44, v44
	v_add_f32_e32 v42, v42, v43
	v_add_f32_e32 v41, v41, v42
	v_add_f32_e32 v40, v40, v41
	s_nop 1
	v_add_f32_dpp v40, v40, v40 quad_perm:[1,0,3,2] row_mask:0xf bank_mask:0xf bound_ctrl:1
	s_nop 1
	v_add_f32_dpp v40, v40, v40 quad_perm:[2,3,0,1] row_mask:0xf bank_mask:0xf bound_ctrl:1
	s_nop 1
	v_add_f32_dpp v40, v40, v40 row_half_mirror row_mask:0xf bank_mask:0xf bound_ctrl:1
	v_fmamk_f32 v40, v40, 0x3c800000, v211
	v_rsq_f32_e32 v40, v40
	v_lshlrev_b32_e32 v41, 16, v36
	v_and_b32_e32 v42, 0xffff0000, v36
	v_mul_f32_e32 v41, v40, v41
	v_mul_f32_e32 v42, v40, v42
	v_cvt_pk_bf16_f32 v36, v41, v42
	v_lshlrev_b32_e32 v41, 16, v37
	v_and_b32_e32 v42, 0xffff0000, v37
	v_mul_f32_e32 v41, v40, v41
	v_mul_f32_e32 v42, v40, v42
	v_cvt_pk_bf16_f32 v37, v41, v42
	v_lshlrev_b32_e32 v41, 16, v38
	v_and_b32_e32 v42, 0xffff0000, v38
	v_mul_f32_e32 v41, v40, v41
	v_mul_f32_e32 v42, v40, v42
	v_cvt_pk_bf16_f32 v38, v41, v42
	v_lshlrev_b32_e32 v41, 16, v39
	v_and_b32_e32 v42, 0xffff0000, v39
	v_mul_f32_e32 v41, v40, v41
	v_mul_f32_e32 v42, v40, v42
	v_cvt_pk_bf16_f32 v39, v41, v42
	global_store_dwordx4 v4, v[36:39], s[8:9]
	s_add_u32 s8, s8, 0x20800
	s_addc_u32 s9, s9, 0
	s_add_i32 s5, s5, 1
	s_cmp_lt_u32 s5, 2
	s_cbranch_scc1 .Lkn_a_half
	s_branch .Lkn_a_next
.Lkn_a_done:
	v_readlane_b32 s2, v128, 0
	v_readlane_b32 s3, v128, 1
	v_readlane_b32 s4, v128, 2
	v_readlane_b32 s5, v128, 3
	v_readlane_b32 s6, v128, 4
	v_readlane_b32 s7, v128, 5
	v_readlane_b32 s8, v128, 6
	v_readlane_b32 s9, v128, 7
	v_readlane_b32 s10, v128, 8
	v_readlane_b32 s11, v128, 9

; #define ATT_LOAD(jt) do { ATT_LOADK(jt); ATT_LOADV(jt); } while (0)
; template <int MODE>
; __device__ __forceinline__ void attn_item(const AttnP& p, int b, int h, int qb, LAS unsigned char* lds) {
;     ...
;     ATT_LOAD(jt_max);
;     ATT_STORE(0, jt_max);
.LBB0_219:
	s_nop 0
	v_mov_b64_e32 v[68:69], v[146:147]
	v_mov_b64_e32 v[70:71], v[148:149]
	s_waitcnt vmcnt(0) lgkmcnt(0)
	v_and_b32_e32 v119, 0xffff0000, v67
	v_and_b32_e32 v131, 0xffff0000, v66
	v_lshlrev_b32_e32 v118, 16, v67
	v_lshlrev_b32_e32 v130, 16, v66
	v_mov_b32_e32 v132, v119
	v_mov_b32_e32 v133, v131
	v_mov_b32_e32 v128, v118
	v_mov_b32_e32 v129, v130
	v_pk_mul_f32 v[132:133], v[132:133], v[132:133]
	v_and_b32_e32 v135, 0xffff0000, v64
	v_pk_fma_f32 v[128:129], v[128:129], v[128:129], v[132:133]
	v_and_b32_e32 v133, 0xffff0000, v65
	v_lshlrev_b32_e32 v132, 16, v65
	v_lshlrev_b32_e32 v134, 16, v64
	v_mov_b32_e32 v138, v135
	v_mov_b32_e32 v139, v133
	v_mov_b32_e32 v136, v134
	v_mov_b32_e32 v137, v132
	v_pk_mul_f32 v[138:139], v[138:139], v[138:139]
	v_mad_u64_u32 v[116:117], s[4:5], v127, s72, v[108:109]
	v_pk_fma_f32 v[136:137], v[136:137], v[136:137], v[138:139]
	v_lshlrev_b32_e32 v108, 1, v116
	v_add_f32_e32 v120, v136, v137
	v_add_f32_e32 v120, v129, v120
	v_add_f32_e32 v120, v128, v120
	v_mul_lo_u32 v117, v127, 24
	v_add_lshl_u32 v116, v116, v117, 1
	v_add_f32_dpp v120, v120, v120 quad_perm:[1,0,3,2] row_mask:0xf bank_mask:0xf bound_ctrl:1
	v_add_u32_e32 v117, 0, v108
	s_mov_b64 s[4:5], -1
	v_add_f32_dpp v120, v120, v120 quad_perm:[2,3,0,1] row_mask:0xf bank_mask:0xf bound_ctrl:1
	s_andn2_b64 vcc, exec, s[0:1]
	s_nop 0
	v_add_f32_dpp v120, v120, v120 row_half_mirror row_mask:0xf bank_mask:0xf bound_ctrl:1
	v_fmamk_f32 v120, v120, 0x3c800000, v211
	v_mov_b32_e32 v120, 1.0
	s_nop 0
	v_pk_mul_f32 v[128:129], v[120:121], v[134:135] op_sel_hi:[0,1]
	v_pk_mul_f32 v[132:133], v[120:121], v[132:133] op_sel_hi:[0,1]
	v_pk_mul_f32 v[130:131], v[120:121], v[130:131] op_sel_hi:[0,1]
	v_pk_mul_f32 v[118:119], v[120:121], v[118:119] op_sel_hi:[0,1]
	v_cvt_pk_bf16_f32 v128, v128, v129
	v_cvt_pk_bf16_f32 v129, v132, v133
	v_cvt_pk_bf16_f32 v130, v130, v131
	v_cvt_pk_bf16_f32 v131, v118, v119
	v_add_u32_e32 v118, 0, v116
	ds_write_b128 v117, v[128:131]
	ds_write_b128 v118, v[68:71] offset:9216
	v_lshlrev_b32_e32 v117, 2, v216
	v_and_b32_e32 v128, 63, v216
	v_or_b32_e32 v129, 0x80, v117
	v_and_b32_e32 v131, 0x100, v117
	s_cbranch_vccnz .LBB0_221
	v_and_b32_e32 v130, 63, v216
	v_or_b32_e32 v118, 0x80, v117
	v_and_b32_e32 v119, 0x100, v117
	s_mov_b64 s[4:5], 0

.LBB0_237:
	s_waitcnt vmcnt(0) lgkmcnt(0)
	s_xor_b32 s22, s35, 1
	s_mulk_i32 s22, 0x5500
	s_add_i32 s22, s22, 0
	s_and_b64 vcc, exec, s[14:15]
	v_add_u32_e32 v13, s22, v108
	v_add_u32_e32 v6, s22, v116
	ds_write_b128 v13, v[64:67]
	ds_write_b128 v6, v[68:71] offset:9216
	s_cbranch_vccnz .LBB0_227
	v_add_f32_e32 v2, v110, v112
	v_mul_f32_e64 v3, |v2|, s40
	v_exp_f32_e32 v3, v3
	v_min_f32_e32 v2, 0, v2
	s_cmp_lg_u32 s30, 2
	v_add_f32_e32 v3, 1.0, v3
	v_cmp_gt_f32_e32 vcc, s78, v3
	s_nop 1
	v_cndmask_b32_e64 v4, 0, 32, vcc
	v_ldexp_f32 v3, v3, v4
	v_log_f32_e32 v3, v3
	v_cndmask_b32_e32 v4, 0, v218, vcc
	v_mul_f32_e32 v5, 0x3f317217, v3
	v_fma_f32 v5, v3, s79, -v5
	v_fmac_f32_e32 v5, 0x3377d1cf, v3
	v_fmac_f32_e32 v5, 0x3f317217, v3
	v_cmp_lt_f32_e64 vcc, |v3|, s37
	s_nop 1
	v_cndmask_b32_e32 v3, v3, v5, vcc
	v_sub_f32_e32 v3, v3, v4
	v_sub_f32_e32 v2, v2, v3
	v_mov_b32_e32 v3, v2
	s_nop 1
	v_add_f32_dpp v3, v3, v3 row_shl:1 row_mask:0xf bank_mask:0xf bound_ctrl:1
	s_nop 1
	v_add_f32_dpp v3, v3, v3 row_shl:2 row_mask:0xf bank_mask:0xf bound_ctrl:1
	s_nop 1
	v_add_f32_dpp v3, v3, v3 row_shl:4 row_mask:0xf bank_mask:0xf bound_ctrl:1
	s_nop 1
	v_add_f32_dpp v3, v3, v3 row_shl:8 row_mask:0xf bank_mask:0xf bound_ctrl:1
	s_nop 1
	v_readlane_b32 s23, v3, 48
	v_readlane_b32 s24, v3, 32
	v_readlane_b32 s25, v3, 16
	s_nop 1
	v_mov_b32_e32 v4, s23
	v_mov_b32_e32 v5, s24
	v_mov_b32_e32 v6, s25
	s_nop 1
	v_add_f32_dpp v3, v4, v3 quad_perm:[0,1,2,3] row_mask:0x7 bank_mask:0xf
	s_nop 1
	v_add_f32_dpp v3, v5, v3 quad_perm:[0,1,2,3] row_mask:0x3 bank_mask:0xf
	s_nop 1
	v_add_f32_dpp v3, v6, v3 quad_perm:[0,1,2,3] row_mask:0x1 bank_mask:0xf
	v_sub_f32_e32 v4, v3, v2
	v_readlane_b32 s23, v3, 0
	v_add_f32_e32 v3, v120, v4
	v_mul_f32_e32 v3, 0x3fb8aa3b, v3
	v_lshl_add_u32 v4, v89, 2, s22
	ds_write_b32 v4, v3 offset:21504
	s_cbranch_scc1 .LBB0_240
	v_readlane_b32 s24, v3, 0
	s_nop 1
	v_mov_b32_e32 v117, s24

; #define PG8_STAGE(bufoff, gbase, voff) do { _Pragma("unroll") for (int _i = 0; _i < 2; ++_i) \
;         __builtin_amdgcn_global_load_lds((const unsigned*)((const char*)(gbase) + (voff)[_i]), (PG8_LAS unsigned*)(lds + (bufoff) + ldsw + _i * 8192), 16, 0, 0); } while (0)
; #define PG8_WAIT_V(n) asm volatile("s_waitcnt vmcnt(" #n ")" ::: "memory")
; #define PG8_BAR __builtin_amdgcn_s_barrier()
; template <class Epi, class Sched, bool ALIGN_EPI = false, bool SP2 = false>
; __device__ __forceinline__ void gemm_phase(PG8_LAS unsigned char* lds, const Gemm g, const Sched& S, const Epi& E) {
;     ...
;     const char* cA = (const char*)g.A + (size_t)cur.pm * tstep; const char* cB = (const char*)g.Bt + (size_t)cur.pn * tstep;
;     S.a_ready(cur);
;     if constexpr (SP2) {
;         PG8_STAGE(PG8_SB(0, 0), cB, voffB); PG8_STAGE(PG8_SB(0, 1), cB + hstep, voffB); PG8_STAGE(PG8_SA(0, 0), cA, voffA); PG8_STAGE(PG8_SA(0, 1), cA + hstep, voffA);
;         if (wr == 1) PG8_BAR;
;         PG8_WAIT_V(2); PG8_BAR;
;         PG8_STAGE(PG8_SB(1, 0), cB + kstep, voffB); PG8_STAGE(PG8_SA(1, 0), cA + kstep, voffA); PG8_STAGE(PG8_SB(1, 1), cB + hstep + kstep, voffB);
;         PG8_WAIT_V(6); PG8_BAR;
;     } else {
;         PG8_STAGE(PG8_SB(0, 0), cB, voffB); PG8_STAGE(PG8_SA(0, 0), cA, voffA); PG8_STAGE(PG8_SB(0, 1), cB + hstep, voffB); PG8_STAGE(PG8_SA(0, 1), cA + hstep, voffA);
;         if (wr == 1) PG8_BAR;
;         PG8_WAIT_V(4); PG8_BAR;
;         PG8_STAGE(PG8_SB(1, 0), cB + kstep, voffB); PG8_STAGE(PG8_SA(1, 0), cA + kstep, voffA); PG8_STAGE(PG8_SB(1, 1), cB + hstep + kstep, voffB);
;         PG8_WAIT_V(6); PG8_BAR;
.LBB0_368:
	s_add_u32 s14, s2, 0x6a00000
	s_addc_u32 s15, s3, 0
	s_lshl_b32 s6, s6, 5
	s_and_b32 s40, s6, 0x60
	s_add_i32 m0, s36, 0x18000
	v_lshl_add_u64 v[8:9], v[8:9], 0, s[96:97]
	s_lshl_b32 s16, s5, 13
	s_lshl_b32 s17, s40, 7
	s_waitcnt vmcnt(2)
	s_barrier
	global_load_lds_dwordx4 v[8:9], off
	v_lshl_add_u64 v[6:7], v[6:7], 0, s[96:97]
	s_add_i32 m0, s36, 0x1a000
	s_add_i32 s41, s36, 0x8000
	s_add_i32 s42, s36, 0xa000
	global_load_lds_dwordx4 v[6:7], off
	v_lshl_add_u64 v[2:3], v[2:3], 0, s[96:97]
	s_mov_b32 m0, s41
	s_add_u32 s6, s0, 0x40080
	global_load_lds_dwordx4 v[2:3], off
	v_lshl_add_u64 v[2:3], v[4:5], 0, s[96:97]
	s_mov_b32 m0, s42
	s_addc_u32 s7, s1, 0
	global_load_lds_dwordx4 v[2:3], off
	s_add_i32 m0, s36, 0x1c000
	v_lshl_add_u64 v[2:3], s[6:7], 0, v[134:135]
	global_load_lds_dwordx4 v[2:3], off
	v_lshl_add_u64 v[2:3], s[6:7], 0, v[130:131]
	s_add_i32 m0, s36, 0x1e000
	s_cmpk_lt_u32 s4, 0x100
	global_load_lds_dwordx4 v[2:3], off
	v_bfe_u32 v2, v0, 4, 2
	v_and_b32_e32 v3, 15, v0
	v_lshlrev_b32_e32 v138, 3, v2
	v_lshlrev_b32_e32 v2, 4, v2
	v_lshlrev_b32_e32 v0, 2, v0
	v_lshl_or_b32 v139, s5, 6, v3
	v_lshl_or_b32 v3, v3, 6, v2
	v_and_b32_e32 v0, 32, v0
	v_bitop3_b32 v6, v3, s16, v0 bitop3:0xde
	v_bitop3_b32 v163, v3, s17, v0 bitop3:0xde
	v_or_b32_e32 v0, s40, v138
	v_cmp_gt_u32_e64 s[6:7], s72, v0
	v_lshlrev_b32_e32 v0, 2, v0
	v_lshl_add_u64 v[4:5], s[2:3], 0, v[0:1]
	s_mov_b64 s[4:5], 0x16e00000
	v_mov_b32_e32 v3, v1
	v_lshlrev_b32_e32 v0, 14, v10
	v_lshl_add_u64 v[140:141], v[4:5], 0, s[4:5]
	v_lshl_add_u64 v[2:3], s[2:3], 0, v[2:3]
	s_mov_b64 s[4:5], 0x1b800000
	v_and_b32_e32 v0, 0xffff8000, v0
	v_lshl_add_u64 v[142:143], v[2:3], 0, s[4:5]
	v_lshl_add_u32 v0, v11, 11, v0
	v_and_b32_e32 v2, 1, v10
	v_lshl_or_b32 v0, v2, 6, v0
	v_lshl_add_u32 v144, v12, 1, v0
	v_lshlrev_b32_e32 v0, 14, v14
	v_and_b32_e32 v0, 0xffff8000, v0
	s_waitcnt vmcnt(6)
	v_lshl_add_u32 v0, v13, 11, v0
	v_and_b32_e32 v2, 1, v14
	v_lshl_or_b32 v0, v2, 6, v0
	v_readlane_b32 s4, v254, 13
	s_cselect_b64 s[16:17], -1, 0
	s_waitcnt lgkmcnt(0)
	s_ashr_i32 s43, s30, 31
	v_mov_b32_e32 v145, v1
	v_lshl_add_u32 v146, v15, 1, v0
	v_mov_b32_e32 v147, v1
	s_mov_b32 s44, 0
	v_add_u32_e32 v166, 0, v6
	v_readlane_b32 s45, v253, 63
	s_mov_b32 s46, s4
	s_barrier
	v_readlane_b32 s5, v254, 14
	s_mov_b64 s[100:101], 0
	s_branch .LBB0_371

; template <class Epi, class Sched, bool ALIGN_EPI = false, bool SP2 = false>
; __device__ __forceinline__ void gemm_phase(PG8_LAS unsigned char* lds, const Gemm g, const Sched& S, const Epi& E) {
;     ...
;     for (;;) {
;         const bool has_next = S.next(ui + 1, nxt);
;         const char* nA = has_next ? (const char*)g.A + (size_t)nxt.pm * tstep : cA; const char* nB = has_next ? (const char*)g.Bt + (size_t)nxt.pn * tstep : cB;
;         for (int t = 0; t < nt; t += 2) {
;             const bool last = (t == nt - 2);
;             const char* a1 = cA + (size_t)(t + 1) * kstep;
;             const char* a2 = last ? nA : cA + (size_t)(t + 2) * kstep; const char* b2 = last ? nB : cB + (size_t)(t + 2) * kstep;
;             const char* a3 = a2 + kstep; const char* b3 = b2 + kstep;
;             if (last && has_next) S.a_ready(nxt);
.LBB0_381:
	s_and_b32 vcc_lo, s45, -2
	s_cmp_eq_u32 vcc_lo, 2
	s_cbranch_scc0 .Lkn_norec_b
	s_lshl_b64 s[100:101], s[100:101], 10
	s_or_b32 s100, s100, 0x200
	s_and_b32 vcc_lo, s45, 1
	s_lshl_b32 vcc_lo, vcc_lo, 8
	s_or_b32 s100, s100, vcc_lo
	s_or_b32 s100, s100, s46

; #define ATT_LOAD(jt) do { ATT_LOADK(jt); ATT_LOADV(jt); } while (0)
; template <int MODE>
; __device__ __forceinline__ void attn_item(const AttnP& p, int b, int h, int qb, LAS unsigned char* lds) {
;     ...
;     ATT_LOAD(jt_max);
;     ATT_STORE(0, jt_max);
.LBB0_494:
	s_or_b64 exec, exec, s[0:1]
	s_lshl_b32 s0, s5, 2
	v_ashrrev_i32_e32 v4, 3, v50
	s_or_b32 s10, s0, 3
	v_add_u32_e32 v229, s8, v4
	v_lshl_add_u32 v0, s10, 6, v229
	v_mov_b64_e32 v[2:3], s[46:47]
	v_mad_i64_i32 v[2:3], s[0:1], v0, s76, v[2:3]
	v_lshlrev_b32_e32 v0, 3, v50
	v_and_b32_e32 v34, 56, v0
	s_lshl_b32 s0, s9, 1
	s_mov_b32 s1, s93
	v_lshl_add_u64 v[2:3], v[2:3], 0, s[0:1]
	v_lshlrev_b32_e32 v0, 1, v34
	v_lshl_add_u64 v[2:3], v[2:3], 0, v[0:1]
	global_load_dwordx4 v[178:181], v[2:3], off offset:1024
	global_load_dwordx4 v[182:185], v[2:3], off offset:1152
	global_load_dwordx4 v[186:189], v[2:3], off offset:2048
	global_load_dwordx4 v[190:193], v[2:3], off offset:2176
	v_mul_lo_u32 v35, v4, 24
	s_movk_i32 s1, 0x88
	v_mad_u64_u32 v[4:5], s[6:7], v4, s1, v[34:35]
	v_lshlrev_b32_e32 v231, 1, v4
	v_add_lshl_u32 v232, v4, v35, 1
	v_add_u32_e32 v36, 64, v4
	v_add_lshl_u32 v234, v36, v35, 1
	v_add_u32_e32 v37, 0, v231
	v_lshlrev_b32_e32 v233, 1, v36
	v_add_u32_e32 v38, 0, v232
	v_add_u32_e32 v39, 0, v233
	v_lshlrev_b32_e32 v230, 2, v48
	v_and_b32_e32 v41, 16, v50
	s_or_b32 s5, s9, 0x200
	s_or_b32 s6, s9, 0x400
	s_or_b32 s1, s4, 31
	v_mul_u32_u24_e32 v235, 0x110, v49
	s_lshl_b32 s4, s2, 2
	v_mad_i32_i24 v236, v48, -4, v49
	s_lshl_b32 s2, s2, 8
	s_add_i32 s11, s3, 0xffffff01
	v_mov_b32_e32 v208, v1
	v_mov_b32_e32 v209, v1
	s_mov_b32 s12, 0
	s_sub_i32 s13, 64, s4
	s_sub_i32 s14, 0xf80, s2
	s_lshl_b32 s92, s5, 1
	s_lshl_b32 s4, s6, 1
	s_waitcnt vmcnt(0) lgkmcnt(0)
	v_and_b32_e32 v3, 0xffff0000, v181
	v_and_b32_e32 v5, 0xffff0000, v180
	v_and_b32_e32 v7, 0xffff0000, v179
	v_and_b32_e32 v9, 0xffff0000, v178
	v_lshlrev_b32_e32 v2, 16, v181
	v_lshlrev_b32_e32 v4, 16, v180
	v_lshlrev_b32_e32 v6, 16, v179
	v_lshlrev_b32_e32 v8, 16, v178
	v_and_b32_e32 v15, 0xffff0000, v183
	v_and_b32_e32 v17, 0xffff0000, v182
	v_mov_b32_e32 v20, v3
	v_mov_b32_e32 v21, v5
	v_mov_b32_e32 v24, v9
	v_mov_b32_e32 v25, v7
	v_and_b32_e32 v11, 0xffff0000, v185
	v_and_b32_e32 v13, 0xffff0000, v184
	v_lshlrev_b32_e32 v14, 16, v183
	v_lshlrev_b32_e32 v16, 16, v182
	v_mov_b32_e32 v18, v2
	v_mov_b32_e32 v19, v4
	v_mov_b32_e32 v22, v8
	v_mov_b32_e32 v23, v6
	v_mov_b32_e32 v32, v17
	v_mov_b32_e32 v33, v15
	v_pk_mul_f32 v[20:21], v[20:21], v[20:21]
	v_pk_mul_f32 v[24:25], v[24:25], v[24:25]
	v_lshlrev_b32_e32 v10, 16, v185
	v_lshlrev_b32_e32 v12, 16, v184
	v_mov_b32_e32 v28, v11
	v_mov_b32_e32 v29, v13
	v_mov_b32_e32 v30, v16
	v_mov_b32_e32 v31, v14
	v_pk_mul_f32 v[32:33], v[32:33], v[32:33]
	v_pk_fma_f32 v[18:19], v[18:19], v[18:19], v[20:21]
	v_pk_fma_f32 v[20:21], v[22:23], v[22:23], v[24:25]
	v_mov_b32_e32 v26, v10
	v_mov_b32_e32 v27, v12
	v_pk_mul_f32 v[28:29], v[28:29], v[28:29]
	v_pk_fma_f32 v[24:25], v[30:31], v[30:31], v[32:33]
	v_add_f32_e32 v0, v20, v21
	v_pk_fma_f32 v[22:23], v[26:27], v[26:27], v[28:29]
	v_add_f32_e32 v20, v24, v25
	v_add_f32_e32 v0, v19, v0
	v_add_f32_e32 v19, v23, v20
	v_add_f32_e32 v0, v18, v0
	v_add_f32_e32 v18, v22, v19
	s_nop 0
	v_add_f32_dpp v0, v0, v0 quad_perm:[1,0,3,2] row_mask:0xf bank_mask:0xf bound_ctrl:1
	v_add_f32_dpp v18, v18, v18 quad_perm:[1,0,3,2] row_mask:0xf bank_mask:0xf bound_ctrl:1
	s_nop 0
	v_add_f32_dpp v0, v0, v0 quad_perm:[2,3,0,1] row_mask:0xf bank_mask:0xf bound_ctrl:1
	v_add_f32_dpp v18, v18, v18 quad_perm:[2,3,0,1] row_mask:0xf bank_mask:0xf bound_ctrl:1
	s_nop 0
	v_add_f32_dpp v0, v0, v0 row_half_mirror row_mask:0xf bank_mask:0xf bound_ctrl:1
	v_fmamk_f32 v0, v0, 0x3c800000, v211
	v_add_f32_dpp v18, v18, v18 row_half_mirror row_mask:0xf bank_mask:0xf bound_ctrl:1
	v_mov_b32_e32 v0, 1.0
	v_fmamk_f32 v18, v18, 0x3c800000, v211
	v_mov_b32_e32 v18, 1.0
	v_pk_mul_f32 v[8:9], v[0:1], v[8:9] op_sel_hi:[0,1]
	v_pk_mul_f32 v[6:7], v[0:1], v[6:7] op_sel_hi:[0,1]
	v_pk_mul_f32 v[4:5], v[0:1], v[4:5] op_sel_hi:[0,1]
	v_pk_mul_f32 v[20:21], v[0:1], v[2:3] op_sel_hi:[0,1]
	v_pk_mul_f32 v[16:17], v[18:19], v[16:17] op_sel_hi:[0,1]
	v_pk_mul_f32 v[14:15], v[18:19], v[14:15] op_sel_hi:[0,1]
	v_pk_mul_f32 v[12:13], v[18:19], v[12:13] op_sel_hi:[0,1]
	v_pk_mul_f32 v[10:11], v[18:19], v[10:11] op_sel_hi:[0,1]
	v_cvt_pk_bf16_f32 v2, v8, v9
	v_cvt_pk_bf16_f32 v3, v6, v7
	v_cvt_pk_bf16_f32 v4, v4, v5
	v_cvt_pk_bf16_f32 v5, v20, v21
	v_add_u32_e32 v0, 0, v234
	v_cvt_pk_bf16_f32 v6, v16, v17
	v_cvt_pk_bf16_f32 v7, v14, v15
	v_cvt_pk_bf16_f32 v8, v12, v13
	v_cvt_pk_bf16_f32 v9, v10, v11
	ds_write_b128 v37, v[2:5]
	ds_write_b128 v38, v[186:189] offset:17408
	ds_write_b128 v39, v[6:9]
	ds_write_b128 v0, v[190:193] offset:17408
	v_lshlrev_b32_e32 v0, 2, v51
	s_waitcnt lgkmcnt(0)
	s_barrier
; #define LAS __attribute__((address_space(3)))
; template <int MODE>
; __device__ __forceinline__ void attn_item(const AttnP& p, int b, int h, int qb, LAS unsigned char* lds) {
;     ...
;     f32x16 O[NC][DV / 32];
; #pragma unroll
;     for (int c = 0; c < NC; ++c)
; #pragma unroll
;         for (int d = 0; d < DV / 32; ++d)
; #pragma unroll
;             for (int i = 0; i < 16; ++i) O[c][d][i] = 0.f;
;     float mrun[NC], lsum[NC];
; #pragma unroll
;     for (int c = 0; c < NC; ++c) { mrun[c] = -1e30f; lsum[c] = 0.f; }
;     ...
;     float mfix = 0.f;
;     if (MODE == 2) mfix = qk2;
;     if (MODE == 0) {
;         float gq_ = fabsf(p.qk_gain[lane]), gk_ = fabsf(p.qk_gain[64 + lane]);
;         const LAS float* tab_ = (const LAS float*)(lds + TAB_OFF);
;         float tm_ = fmaxf(fmaxf(fabsf(tab_[lane]), fabsf(tab_[64 + lane])), fmaxf(fabsf(tab_[128 + lane]), fabsf(tab_[192 + lane])));
; #pragma unroll
;         for (int o_ = 1; o_ < 64; o_ <<= 1) { gq_ = fmaxf(gq_, __shfl_xor(gq_, o_)); gk_ = fmaxf(gk_, __shfl_xor(gk_, o_)); tm_ = fmaxf(tm_, __shfl_xor(tm_, o_)); }
;         mfix = 8.0f * gq_ * gk_ * LOG2E * 1.02f + tm_;
;     }
	global_load_dword v35, v0, s[40:41]
	global_load_dword v40, v0, s[40:41] offset:256
	v_add_u32_e32 v0, 0, v0
	v_add_u32_e32 v0, 0x12a00, v0
	ds_read2st64_b32 v[36:37], v0 offset1:1
	ds_read2st64_b32 v[38:39], v0 offset0:2 offset1:3
	v_lshrrev_b32_e32 v18, 2, v50
	v_lshlrev_b32_e32 v19, 2, v50
	v_and_or_b32 v42, v18, 3, v230
	v_and_b32_e32 v43, 12, v19
	s_waitcnt lgkmcnt(0)
	v_max_f32_e64 v39, |v39|, |v39|
	v_max_f32_e64 v38, |v38|, |v38|
	v_max_f32_e32 v38, v38, v39
	v_max3_f32 v36, |v36|, |v37|, v38
	ds_bpermute_b32 v37, v221, v36
	v_mul_u32_u24_e32 v0, 0xa0, v42
	v_or3_b32 v0, v43, v41, v0
	v_lshlrev_b32_e32 v237, 1, v0
	v_mov_b32_e32 v16, v1
	s_waitcnt lgkmcnt(0)
	v_max_f32_e32 v0, v37, v37
	v_max_f32_e32 v0, v36, v0
	ds_bpermute_b32 v38, v222, v0
	v_mov_b32_e32 v17, v1
	v_mov_b32_e32 v2, v1
	v_mov_b32_e32 v3, v1
	v_mov_b32_e32 v4, v1
	s_waitcnt lgkmcnt(0)
	v_max_f32_e32 v38, v38, v38
	v_max_f32_e32 v0, v0, v38
	ds_bpermute_b32 v38, v223, v0
	v_mov_b32_e32 v5, v1
	v_mov_b32_e32 v6, v1
	v_mov_b32_e32 v7, v1
	v_mov_b32_e32 v8, v1
	s_waitcnt lgkmcnt(0)
	v_max_f32_e32 v38, v38, v38
	v_max_f32_e32 v0, v0, v38
	ds_bpermute_b32 v38, v224, v0
	v_mov_b32_e32 v9, v1
	v_mov_b32_e32 v10, v1
	v_mov_b32_e32 v11, v1
	v_mov_b32_e32 v12, v1
	s_waitcnt lgkmcnt(0)
	v_max_f32_e32 v38, v38, v38
	v_max_f32_e32 v0, v0, v38
	ds_bpermute_b32 v38, v225, v0
	v_mov_b32_e32 v13, v1
	v_mov_b32_e32 v14, v1
	v_mov_b32_e32 v15, v1
	v_mov_b64_e32 v[32:33], v[16:17]
	s_waitcnt lgkmcnt(0)
	v_max_f32_e32 v38, v38, v38
	v_max_f32_e32 v38, v0, v38
	v_mov_b64_e32 v[80:81], v[16:17]
	v_mov_b64_e32 v[112:113], v[16:17]
	v_mov_b64_e32 v[64:65], v[16:17]
	v_mov_b64_e32 v[96:97], v[16:17]
	v_mov_b64_e32 v[128:129], v[16:17]
	v_mov_b64_e32 v[30:31], v[14:15]
	v_mov_b64_e32 v[28:29], v[12:13]
	v_mov_b64_e32 v[26:27], v[10:11]
	v_mov_b64_e32 v[24:25], v[8:9]
	v_mov_b64_e32 v[22:23], v[6:7]
	v_mov_b64_e32 v[20:21], v[4:5]
	v_mov_b64_e32 v[18:19], v[2:3]
	v_mov_b64_e32 v[78:79], v[14:15]
	v_mov_b64_e32 v[76:77], v[12:13]
	v_mov_b64_e32 v[74:75], v[10:11]
	v_mov_b64_e32 v[72:73], v[8:9]
	v_mov_b64_e32 v[70:71], v[6:7]
	v_mov_b64_e32 v[68:69], v[4:5]
	v_mov_b64_e32 v[66:67], v[2:3]
	v_mov_b64_e32 v[110:111], v[14:15]
	v_mov_b64_e32 v[108:109], v[12:13]
	v_mov_b64_e32 v[106:107], v[10:11]
	v_mov_b64_e32 v[104:105], v[8:9]
	v_mov_b64_e32 v[102:103], v[6:7]
	v_mov_b64_e32 v[100:101], v[4:5]
	v_mov_b64_e32 v[98:99], v[2:3]
	v_add_u32_e32 v238, 0x2800, v237
	v_add_u32_e32 v239, 0x3c00, v237
	v_add_u32_e32 v240, 0x1400, v237
	v_mov_b64_e32 v[62:63], v[14:15]
	v_mov_b64_e32 v[60:61], v[12:13]
	v_mov_b64_e32 v[58:59], v[10:11]
	s_waitcnt vmcnt(1)
	v_and_b32_e32 v36, 0x7fffffff, v35
	s_waitcnt vmcnt(0)
	v_and_b32_e32 v37, 0x7fffffff, v40
	ds_bpermute_b32 v36, v221, v36
	ds_bpermute_b32 v37, v221, v37
	v_max_f32_e64 v35, |v35|, |v35|
	v_max_f32_e64 v39, |v40|, |v40|
	ds_bpermute_b32 v40, v226, v38
	s_waitcnt lgkmcnt(2)
	v_max_f32_e32 v36, v36, v36
	s_waitcnt lgkmcnt(1)
	v_max_f32_e32 v37, v37, v37
	v_max_f32_e32 v35, v35, v36
	v_max_f32_e32 v36, v39, v37
	ds_bpermute_b32 v37, v222, v35
	ds_bpermute_b32 v39, v222, v36
	v_mov_b64_e32 v[56:57], v[8:9]
	v_mov_b64_e32 v[54:55], v[6:7]
	v_mov_b64_e32 v[52:53], v[4:5]
	s_waitcnt lgkmcnt(1)
	v_max_f32_e32 v37, v37, v37
	s_waitcnt lgkmcnt(0)
	v_max_f32_e32 v39, v39, v39
	v_max_f32_e32 v35, v35, v37
	v_max_f32_e32 v36, v36, v39
	ds_bpermute_b32 v37, v223, v35
	ds_bpermute_b32 v39, v223, v36
	v_mov_b64_e32 v[50:51], v[2:3]
	v_mov_b64_e32 v[94:95], v[14:15]
	v_mov_b64_e32 v[92:93], v[12:13]
	s_waitcnt lgkmcnt(1)
	v_max_f32_e32 v37, v37, v37
	s_waitcnt lgkmcnt(0)
	v_max_f32_e32 v39, v39, v39
	v_max_f32_e32 v35, v35, v37
	v_max_f32_e32 v36, v36, v39
	ds_bpermute_b32 v37, v224, v35
	ds_bpermute_b32 v39, v224, v36
	v_mov_b64_e32 v[90:91], v[10:11]
	v_mov_b64_e32 v[88:89], v[8:9]
	v_mov_b64_e32 v[86:87], v[6:7]
	s_waitcnt lgkmcnt(1)
	v_max_f32_e32 v37, v37, v37
	s_waitcnt lgkmcnt(0)
	v_max_f32_e32 v39, v39, v39
	v_max_f32_e32 v35, v35, v37
	v_max_f32_e32 v36, v36, v39
	ds_bpermute_b32 v37, v225, v35
	ds_bpermute_b32 v39, v225, v36
	v_mov_b64_e32 v[84:85], v[4:5]
	v_mov_b64_e32 v[82:83], v[2:3]
	v_mov_b64_e32 v[126:127], v[14:15]
	s_waitcnt lgkmcnt(1)
	v_max_f32_e32 v0, v37, v37
	s_waitcnt lgkmcnt(0)
	v_max_f32_e32 v37, v39, v39
	v_max_f32_e32 v35, v35, v0
	v_max_f32_e32 v36, v36, v37
	ds_bpermute_b32 v37, v226, v35
	ds_bpermute_b32 v39, v226, v36
	v_lshlrev_b32_e32 v0, 1, v34
	v_max_f32_e32 v34, v40, v40
	v_max_f32_e32 v241, v38, v34
	s_waitcnt lgkmcnt(1)
	v_max_f32_e32 v34, v37, v37
	s_waitcnt lgkmcnt(0)
	v_max_f32_e32 v37, v39, v39
	v_max_f32_e32 v34, v35, v34
	v_max_f32_e32 v35, v36, v37
	v_mul_f32_e32 v34, 0x41000000, v34
	v_mul_f32_e32 v34, v35, v34
	v_mul_f32_e32 v34, 0x3fb8aa3b, v34
	v_fmac_f32_e32 v241, 0x3f828f5c, v34
	v_mov_b64_e32 v[48:49], v[16:17]
	v_mov_b64_e32 v[46:47], v[14:15]
	v_mov_b64_e32 v[44:45], v[12:13]
	v_mov_b64_e32 v[42:43], v[10:11]
	v_mov_b64_e32 v[40:41], v[8:9]
	v_mov_b64_e32 v[38:39], v[6:7]
	v_mov_b64_e32 v[36:37], v[4:5]
	v_mov_b64_e32 v[34:35], v[2:3]
	v_mov_b64_e32 v[124:125], v[12:13]
	v_mov_b64_e32 v[122:123], v[10:11]
	v_mov_b64_e32 v[120:121], v[8:9]
	v_mov_b64_e32 v[118:119], v[6:7]
	v_mov_b64_e32 v[116:117], v[4:5]
	v_mov_b64_e32 v[114:115], v[2:3]
	v_mov_b32_e32 v243, 0x12dfc
	ds_read_b32 v241, v243
	s_waitcnt lgkmcnt(0)
	s_branch .LBB0_496

; #define LAS __attribute__((address_space(3)))
; #define MFMA32(a, b, c) __builtin_amdgcn_mfma_f32_32x32x16_bf16((a), (b), (c), 0, 0, 0)
; __device__ __forceinline__ s16x4 vtr(const LAS unsigned char* p) { return __builtin_bit_cast(s16x4, __builtin_amdgcn_ds_read_tr16_b64_v4i16((LAS v4i16_t*)p)); }
; template <int MODE>
; __device__ __forceinline__ void attn_item(const AttnP& p, int b, int h, int qb, LAS unsigned char* lds) {
;     ...
;                         if (qw - (kp0 + 31) >= 128) {
;                             const float cb = tab[255] - mfix;
; #pragma unroll
;                             for (int c = 0; c < NC; ++c) { ATT_QK(c, cb); ATT_TAIL(c); }
;     ...
; #pragma unroll
;                 for (int t2 = 0; t2 < 2; ++t2)
; #pragma unroll
;                     for (int d = 0; d < DV / 32; ++d) {
;                         const LAS unsigned char* vp = vtb + ((32 * kb2 + 16 * t2 + 4 * hh + ((lane & 15) >> 2)) * VPT + d * 32 + 16 * ((lane >> 4) & 1) + 4 * (lane & 3)) * 2;
;                         const s16x4 lo = vtr(vp), hi = vtr(vp + 8 * VPT * 2);
;                         const bf16x8 va = __builtin_shufflevector(lo, hi, 0, 1, 2, 3, 4, 5, 6, 7);
; #pragma unroll
;                         for (int c = 0; c < NC; ++c) O[c][d] = MFMA32(va, pb[c][t2], O[c][d]);
;                     }
.LBB0_575:
	s_waitcnt vmcnt(0) lgkmcnt(0)
	v_and_b32_e32 v135, 0xffff0000, v181
	v_and_b32_e32 v133, 0xffff0000, v180
	v_lshlrev_b32_e32 v134, 16, v181
	v_lshlrev_b32_e32 v132, 16, v180
	v_mov_b32_e32 v136, v135
	v_mov_b32_e32 v137, v133
	v_mov_b32_e32 v130, v134
	v_mov_b32_e32 v131, v132
	v_pk_mul_f32 v[136:137], v[136:137], v[136:137]
	v_and_b32_e32 v139, 0xffff0000, v178
	v_pk_fma_f32 v[130:131], v[130:131], v[130:131], v[136:137]
	v_and_b32_e32 v137, 0xffff0000, v179
	v_lshlrev_b32_e32 v136, 16, v179
	v_lshlrev_b32_e32 v138, 16, v178
	v_mov_b32_e32 v142, v139
	v_mov_b32_e32 v143, v137
	v_mov_b32_e32 v140, v138
	v_mov_b32_e32 v141, v136
	v_pk_mul_f32 v[142:143], v[142:143], v[142:143]
	s_xor_b32 s2, s5, 1
	v_pk_fma_f32 v[140:141], v[140:141], v[140:141], v[142:143]
	s_mul_i32 s2, s2, 0x9500
	v_add_f32_e32 v140, v140, v141
	v_add_f32_e32 v131, v131, v140
	v_add_f32_e32 v130, v130, v131
	s_add_i32 s2, s2, 0
	s_nop 0
	v_add_f32_dpp v130, v130, v130 quad_perm:[1,0,3,2] row_mask:0xf bank_mask:0xf bound_ctrl:1
	s_nop 1
	v_add_f32_dpp v130, v130, v130 quad_perm:[2,3,0,1] row_mask:0xf bank_mask:0xf bound_ctrl:1
	s_nop 1
	v_add_f32_dpp v130, v130, v130 row_half_mirror row_mask:0xf bank_mask:0xf bound_ctrl:1
	v_fmamk_f32 v130, v130, 0x3c800000, v211
	v_mov_b32_e32 v140, 1.0
	s_nop 0
	v_pk_mul_f32 v[130:131], v[140:141], v[138:139] op_sel_hi:[0,1]
	v_pk_mul_f32 v[136:137], v[140:141], v[136:137] op_sel_hi:[0,1]
	v_pk_mul_f32 v[132:133], v[140:141], v[132:133] op_sel_hi:[0,1]
	v_pk_mul_f32 v[134:135], v[140:141], v[134:135] op_sel_hi:[0,1]
	v_cvt_pk_bf16_f32 v130, v130, v131
	v_cvt_pk_bf16_f32 v131, v136, v137
	v_cvt_pk_bf16_f32 v132, v132, v133
	v_cvt_pk_bf16_f32 v133, v134, v135
	v_add_u32_e32 v134, s2, v231
	ds_write_b128 v134, v[130:133]
	v_and_b32_e32 v135, 0xffff0000, v185
	v_and_b32_e32 v133, 0xffff0000, v184
	v_add_u32_e32 v130, s2, v232
	v_lshlrev_b32_e32 v134, 16, v185
	v_lshlrev_b32_e32 v132, 16, v184
	v_mov_b32_e32 v136, v135
	v_mov_b32_e32 v137, v133
	ds_write_b128 v130, v[186:189] offset:17408
	v_mov_b32_e32 v130, v134
	v_mov_b32_e32 v131, v132
	v_pk_mul_f32 v[136:137], v[136:137], v[136:137]
	v_and_b32_e32 v139, 0xffff0000, v182
	v_pk_fma_f32 v[130:131], v[130:131], v[130:131], v[136:137]
	v_and_b32_e32 v137, 0xffff0000, v183
	v_lshlrev_b32_e32 v136, 16, v183
	v_lshlrev_b32_e32 v138, 16, v182
	v_mov_b32_e32 v142, v139
	v_mov_b32_e32 v143, v137
	v_mov_b32_e32 v140, v138
	v_mov_b32_e32 v141, v136
	v_pk_mul_f32 v[142:143], v[142:143], v[142:143]
	s_nop 0
	v_pk_fma_f32 v[140:141], v[140:141], v[140:141], v[142:143]
	s_nop 0
	v_add_f32_e32 v140, v140, v141
	v_add_f32_e32 v131, v131, v140
	v_add_f32_e32 v130, v130, v131
	s_nop 1
	v_add_f32_dpp v130, v130, v130 quad_perm:[1,0,3,2] row_mask:0xf bank_mask:0xf bound_ctrl:1
	s_nop 1
	v_add_f32_dpp v130, v130, v130 quad_perm:[2,3,0,1] row_mask:0xf bank_mask:0xf bound_ctrl:1
	s_nop 1
	v_add_f32_dpp v130, v130, v130 row_half_mirror row_mask:0xf bank_mask:0xf bound_ctrl:1
	v_fmamk_f32 v130, v130, 0x3c800000, v211
	v_mov_b32_e32 v140, 1.0
	s_nop 0
	v_pk_mul_f32 v[130:131], v[140:141], v[138:139] op_sel_hi:[0,1]
	v_pk_mul_f32 v[136:137], v[140:141], v[136:137] op_sel_hi:[0,1]
	v_pk_mul_f32 v[132:133], v[140:141], v[132:133] op_sel_hi:[0,1]
	v_pk_mul_f32 v[134:135], v[140:141], v[134:135] op_sel_hi:[0,1]
	v_cvt_pk_bf16_f32 v130, v130, v131
	v_cvt_pk_bf16_f32 v131, v136, v137
	v_cvt_pk_bf16_f32 v132, v132, v133
	v_cvt_pk_bf16_f32 v133, v134, v135
	v_add_u32_e32 v134, s2, v233
	ds_write_b128 v134, v[130:133]
	v_add_u32_e32 v130, s2, v234
	ds_write_b128 v130, v[190:193] offset:17408
	s_branch .LBB0_495
.Lfar_tile:
	s_andn2_b64 vcc, exec, s[6:7]
	s_cbranch_vccnz .Lfar_tile_last
	s_xor_b32 s2, s5, 1
	s_mul_i32 s2, s2, 0x9500
	v_add_u32_e32 v243, v242, v235
	ds_read_b128 v[244:247], v243 offset:8704
	ds_read_b128 v[248:251], v243 offset:8736
	ds_read_b128 v[194:197], v243 offset:8768
	ds_read_b128 v[198:201], v243 offset:8800
	ds_read_b128 v[202:205], v243 offset:8832
	ds_read_b128 v[214:217], v207 offset:4096
	v_add_u32_e32 v218, s15, v238
	v_add_u32_e32 v219, s15, v239
	s_waitcnt lgkmcnt(5)
	v_mfma_f32_32x32x16_bf16 v[146:161], v[244:247], v[162:165], 0
	s_waitcnt lgkmcnt(4)
	v_mfma_f32_32x32x16_bf16 v[146:161], v[248:251], v[166:169], v[146:161]
	ds_read_b128 v[244:247], v243 offset:8864
	ds_read_b128 v[248:251], v207 offset:5120
	s_waitcnt lgkmcnt(5)
	v_mfma_f32_32x32x16_bf16 v[146:161], v[194:197], v[170:173], v[146:161]
	s_waitcnt lgkmcnt(4)
	v_mfma_f32_32x32x16_bf16 v[146:161], v[198:201], v[174:177], v[146:161]
	ds_read_b128 v[194:197], v243 offset:8896
	ds_read_b128 v[198:201], v207 offset:6144
	s_waitcnt lgkmcnt(4)
	v_mfma_f32_32x32x16_bf16 v[130:145], v[202:205], v[214:217], 0
	ds_read_b128 v[202:205], v243 offset:8928
	ds_read_b128 v[214:217], v207 offset:7168
	s_waitcnt lgkmcnt(4)
	v_mfma_f32_32x32x16_bf16 v[130:145], v[244:247], v[248:251], v[130:145]
	ds_read_b64_tr_b16 v[244:245], v218 offset:17408
	ds_read_b64_tr_b16 v[246:247], v218 offset:19968
	ds_read_b64_tr_b16 v[248:249], v218 offset:17472
	ds_read_b64_tr_b16 v[250:251], v218 offset:20032
	v_exp_f32_e32 v146, v146
	v_exp_f32_e32 v147, v147
	v_exp_f32_e32 v148, v148
	v_add_f32_e32 v220, v146, v147
	v_exp_f32_e32 v149, v149
	v_add_f32_e32 v220, v148, v220
	v_exp_f32_e32 v150, v150
	s_waitcnt lgkmcnt(6)
	v_mfma_f32_32x32x16_bf16 v[130:145], v[194:197], v[198:201], v[130:145]
	ds_read_b64_tr_b16 v[194:195], v218 offset:17536
	ds_read_b64_tr_b16 v[196:197], v218 offset:20096
	ds_read_b64_tr_b16 v[198:199], v218 offset:17600
	ds_read_b64_tr_b16 v[200:201], v218 offset:20160
	v_add_f32_e32 v220, v149, v220
	v_exp_f32_e32 v151, v151
	v_add_f32_e32 v220, v150, v220
	v_exp_f32_e32 v152, v152
	v_add_f32_e32 v220, v151, v220
	v_exp_f32_e32 v153, v153
	s_waitcnt lgkmcnt(8)
; #define LAS __attribute__((address_space(3)))
; #define MFMA32(a, b, c) __builtin_amdgcn_mfma_f32_32x32x16_bf16((a), (b), (c), 0, 0, 0)
; __device__ __forceinline__ s16x4 vtr(const LAS unsigned char* p) { return __builtin_bit_cast(s16x4, __builtin_amdgcn_ds_read_tr16_b64_v4i16((LAS v4i16_t*)p)); }
; template <int MODE>
; __device__ __forceinline__ void attn_item(const AttnP& p, int b, int h, int qb, LAS unsigned char* lds) {
;     ...
;                         if (qw - (kp0 + 31) >= 128) {
;                             const float cb = tab[255] - mfix;
; #pragma unroll
;                             for (int c = 0; c < NC; ++c) { ATT_QK(c, cb); ATT_TAIL(c); }
;     ...
; #pragma unroll
;                 for (int t2 = 0; t2 < 2; ++t2)
; #pragma unroll
;                     for (int d = 0; d < DV / 32; ++d) {
;                         const LAS unsigned char* vp = vtb + ((32 * kb2 + 16 * t2 + 4 * hh + ((lane & 15) >> 2)) * VPT + d * 32 + 16 * ((lane >> 4) & 1) + 4 * (lane & 3)) * 2;
;                         const s16x4 lo = vtr(vp), hi = vtr(vp + 8 * VPT * 2);
;                         const bf16x8 va = __builtin_shufflevector(lo, hi, 0, 1, 2, 3, 4, 5, 6, 7);
; #pragma unroll
;                         for (int c = 0; c < NC; ++c) O[c][d] = MFMA32(va, pb[c][t2], O[c][d]);
;                     }
	v_mfma_f32_32x32x16_bf16 v[130:145], v[202:205], v[214:217], v[130:145]
	ds_read_b64_tr_b16 v[202:203], v219 offset:17408
	ds_read_b64_tr_b16 v[204:205], v219 offset:19968
	ds_read_b64_tr_b16 v[214:215], v219 offset:17472
	ds_read_b64_tr_b16 v[216:217], v219 offset:20032
	v_add_f32_e32 v220, v152, v220
	v_cvt_pk_bf16_f32 v146, v146, v147
	v_add_f32_e32 v220, v153, v220
	v_cvt_pk_bf16_f32 v147, v148, v149
	v_cvt_pk_bf16_f32 v148, v150, v151
	v_cvt_pk_bf16_f32 v149, v152, v153
	s_nop 1
	s_waitcnt lgkmcnt(10)
	v_mfma_f32_32x32x16_bf16 v[114:129], v[244:247], v[146:149], v[114:129]
	v_exp_f32_e32 v154, v154
	v_exp_f32_e32 v155, v155
	v_add_f32_e32 v220, v154, v220
	v_exp_f32_e32 v156, v156
	v_add_f32_e32 v220, v155, v220
	v_exp_f32_e32 v157, v157
	s_waitcnt lgkmcnt(8)
	v_mfma_f32_32x32x16_bf16 v[82:97], v[248:251], v[146:149], v[82:97]
	v_add_f32_e32 v220, v156, v220
	v_exp_f32_e32 v158, v158
	v_add_f32_e32 v220, v157, v220
	v_exp_f32_e32 v159, v159
	v_add_f32_e32 v220, v158, v220
	s_waitcnt lgkmcnt(6)
	v_mfma_f32_32x32x16_bf16 v[50:65], v[194:197], v[146:149], v[50:65]
	v_exp_f32_e32 v160, v160
	v_add_f32_e32 v220, v159, v220
	v_exp_f32_e32 v161, v161
	v_add_f32_e32 v220, v160, v220
	v_cvt_pk_bf16_f32 v150, v154, v155
	s_waitcnt lgkmcnt(4)
	v_mfma_f32_32x32x16_bf16 v[34:49], v[198:201], v[146:149], v[34:49]
	v_add_f32_e32 v220, v161, v220
	v_cvt_pk_bf16_f32 v151, v156, v157
	v_cvt_pk_bf16_f32 v152, v158, v159
	v_cvt_pk_bf16_f32 v153, v160, v161
	v_add_f32_e32 v209, v209, v220
	ds_read_b64_tr_b16 v[154:155], v219 offset:17536
	ds_read_b64_tr_b16 v[156:157], v219 offset:20096
	ds_read_b64_tr_b16 v[158:159], v219 offset:17600
	ds_read_b64_tr_b16 v[160:161], v219 offset:20160
	s_waitcnt lgkmcnt(6)
	v_mfma_f32_32x32x16_bf16 v[114:129], v[202:205], v[150:153], v[114:129]
	v_exp_f32_e32 v130, v130
	v_exp_f32_e32 v131, v131
	v_exp_f32_e32 v132, v132
	v_add_f32_e32 v213, v130, v131
	v_exp_f32_e32 v133, v133
	s_waitcnt lgkmcnt(4)
	v_mfma_f32_32x32x16_bf16 v[82:97], v[214:217], v[150:153], v[82:97]
	v_add_f32_e32 v213, v132, v213
	v_exp_f32_e32 v134, v134
	v_add_f32_e32 v213, v133, v213
	v_exp_f32_e32 v135, v135
	v_add_f32_e32 v213, v134, v213
	s_waitcnt lgkmcnt(2)
	v_mfma_f32_32x32x16_bf16 v[50:65], v[154:157], v[150:153], v[50:65]
	v_exp_f32_e32 v136, v136
	v_add_f32_e32 v213, v135, v213
	v_exp_f32_e32 v137, v137
	v_add_f32_e32 v213, v136, v213
	v_cvt_pk_bf16_f32 v130, v130, v131
	s_waitcnt lgkmcnt(0)
	v_mfma_f32_32x32x16_bf16 v[34:49], v[158:161], v[150:153], v[34:49]
	v_add_f32_e32 v213, v137, v213
	v_cvt_pk_bf16_f32 v131, v132, v133
	v_cvt_pk_bf16_f32 v132, v134, v135
	v_cvt_pk_bf16_f32 v133, v136, v137
	s_nop 1
	v_mfma_f32_32x32x16_bf16 v[98:113], v[244:247], v[130:133], v[98:113]
	v_exp_f32_e32 v138, v138
	v_exp_f32_e32 v139, v139
	v_add_f32_e32 v213, v138, v213
	v_exp_f32_e32 v140, v140
	v_add_f32_e32 v213, v139, v213
	v_exp_f32_e32 v141, v141
	ds_read_b128 v[244:247], v243 offset:0
	v_mfma_f32_32x32x16_bf16 v[66:81], v[248:251], v[130:133], v[66:81]
	v_add_f32_e32 v213, v140, v213
	v_exp_f32_e32 v142, v142
	v_add_f32_e32 v213, v141, v213
	v_exp_f32_e32 v143, v143
	v_add_f32_e32 v213, v142, v213
	ds_read_b128 v[248:251], v243 offset:32
	v_mfma_f32_32x32x16_bf16 v[18:33], v[194:197], v[130:133], v[18:33]
	v_exp_f32_e32 v144, v144
	v_add_f32_e32 v213, v143, v213
	v_exp_f32_e32 v145, v145
	v_add_f32_e32 v213, v144, v213
	v_cvt_pk_bf16_f32 v134, v138, v139
	ds_read_b128 v[194:197], v243 offset:64
	v_mfma_f32_32x32x16_bf16 v[2:17], v[198:201], v[130:133], v[2:17]
	v_add_f32_e32 v213, v145, v213
	v_cvt_pk_bf16_f32 v135, v140, v141
	v_cvt_pk_bf16_f32 v136, v142, v143
	v_cvt_pk_bf16_f32 v137, v144, v145
	v_add_f32_e32 v208, v208, v213
	ds_read_b128 v[198:201], v243 offset:96
	s_nop 1
	v_mfma_f32_32x32x16_bf16 v[98:113], v[202:205], v[134:137], v[98:113]
	s_waitcnt vmcnt(3)
	v_add_u32_e32 v139, s2, v231
	ds_write_b128 v139, v[178:181]
	ds_read_b128 v[202:205], v243 offset:128
	v_mfma_f32_32x32x16_bf16 v[66:81], v[214:217], v[134:137], v[66:81]
	ds_read_b128 v[214:217], v207 offset:4096
	v_mfma_f32_32x32x16_bf16 v[18:33], v[154:157], v[134:137], v[18:33]
	v_mfma_f32_32x32x16_bf16 v[2:17], v[158:161], v[134:137], v[2:17]
	v_add_u32_e32 v218, s15, v237
	v_add_u32_e32 v219, s15, v240
	s_waitcnt lgkmcnt(6)
	v_mfma_f32_32x32x16_bf16 v[146:161], v[244:247], v[162:165], 0
	s_waitcnt lgkmcnt(5)
	v_mfma_f32_32x32x16_bf16 v[146:161], v[248:251], v[166:169], v[146:161]
	ds_read_b128 v[244:247], v243 offset:160
	ds_read_b128 v[248:251], v207 offset:5120
	s_waitcnt lgkmcnt(6)
	v_mfma_f32_32x32x16_bf16 v[146:161], v[194:197], v[170:173], v[146:161]
	s_waitcnt lgkmcnt(5)
	v_mfma_f32_32x32x16_bf16 v[146:161], v[198:201], v[174:177], v[146:161]
	ds_read_b128 v[194:197], v243 offset:192
	ds_read_b128 v[198:201], v207 offset:6144
	s_waitcnt lgkmcnt(4)
	v_mfma_f32_32x32x16_bf16 v[130:145], v[202:205], v[214:217], 0
	ds_read_b128 v[202:205], v243 offset:224
	ds_read_b128 v[214:217], v207 offset:7168
	s_waitcnt lgkmcnt(4)
; #define LAS __attribute__((address_space(3)))
; #define MFMA32(a, b, c) __builtin_amdgcn_mfma_f32_32x32x16_bf16((a), (b), (c), 0, 0, 0)
; __device__ __forceinline__ s16x4 vtr(const LAS unsigned char* p) { return __builtin_bit_cast(s16x4, __builtin_amdgcn_ds_read_tr16_b64_v4i16((LAS v4i16_t*)p)); }
; template <int MODE>
; __device__ __forceinline__ void attn_item(const AttnP& p, int b, int h, int qb, LAS unsigned char* lds) {
;     ...
; #pragma unroll
;                 for (int t2 = 0; t2 < 2; ++t2)
; #pragma unroll
;                     for (int d = 0; d < DV / 32; ++d) {
;                         const LAS unsigned char* vp = vtb + ((32 * kb2 + 16 * t2 + 4 * hh + ((lane & 15) >> 2)) * VPT + d * 32 + 16 * ((lane >> 4) & 1) + 4 * (lane & 3)) * 2;
;                         const s16x4 lo = vtr(vp), hi = vtr(vp + 8 * VPT * 2);
;                         const bf16x8 va = __builtin_shufflevector(lo, hi, 0, 1, 2, 3, 4, 5, 6, 7);
; #pragma unroll
;                         for (int c = 0; c < NC; ++c) O[c][d] = MFMA32(va, pb[c][t2], O[c][d]);
;                     }
	v_mfma_f32_32x32x16_bf16 v[130:145], v[244:247], v[248:251], v[130:145]
	ds_read_b64_tr_b16 v[244:245], v218 offset:17408
	ds_read_b64_tr_b16 v[246:247], v218 offset:19968
	ds_read_b64_tr_b16 v[248:249], v218 offset:17472
	ds_read_b64_tr_b16 v[250:251], v218 offset:20032
	v_exp_f32_e32 v146, v146
	v_exp_f32_e32 v147, v147
	v_exp_f32_e32 v148, v148
	v_add_f32_e32 v220, v146, v147
	v_exp_f32_e32 v149, v149
	v_add_f32_e32 v220, v148, v220
	v_exp_f32_e32 v150, v150
	s_waitcnt lgkmcnt(6)
	v_mfma_f32_32x32x16_bf16 v[130:145], v[194:197], v[198:201], v[130:145]
	ds_read_b64_tr_b16 v[194:195], v218 offset:17536
	ds_read_b64_tr_b16 v[196:197], v218 offset:20096
	ds_read_b64_tr_b16 v[198:199], v218 offset:17600
	ds_read_b64_tr_b16 v[200:201], v218 offset:20160
	v_add_f32_e32 v220, v149, v220
	v_exp_f32_e32 v151, v151
	v_add_f32_e32 v220, v150, v220
	v_exp_f32_e32 v152, v152
	v_add_f32_e32 v220, v151, v220
	v_exp_f32_e32 v153, v153
	s_waitcnt lgkmcnt(8)
	v_mfma_f32_32x32x16_bf16 v[130:145], v[202:205], v[214:217], v[130:145]
	ds_read_b64_tr_b16 v[202:203], v219 offset:17408
	ds_read_b64_tr_b16 v[204:205], v219 offset:19968
	ds_read_b64_tr_b16 v[214:215], v219 offset:17472
	ds_read_b64_tr_b16 v[216:217], v219 offset:20032
	v_add_f32_e32 v220, v152, v220
	v_cvt_pk_bf16_f32 v146, v146, v147
	v_add_f32_e32 v220, v153, v220
	v_cvt_pk_bf16_f32 v147, v148, v149
	v_cvt_pk_bf16_f32 v148, v150, v151
	v_cvt_pk_bf16_f32 v149, v152, v153
	s_nop 1
	s_waitcnt lgkmcnt(10)
	v_mfma_f32_32x32x16_bf16 v[114:129], v[244:247], v[146:149], v[114:129]
	v_exp_f32_e32 v154, v154
	v_exp_f32_e32 v155, v155
	v_add_f32_e32 v220, v154, v220
	v_exp_f32_e32 v156, v156
	v_add_f32_e32 v220, v155, v220
	v_exp_f32_e32 v157, v157
	s_waitcnt lgkmcnt(8)
	v_mfma_f32_32x32x16_bf16 v[82:97], v[248:251], v[146:149], v[82:97]
	v_add_f32_e32 v220, v156, v220
	v_exp_f32_e32 v158, v158
	v_add_f32_e32 v220, v157, v220
	v_exp_f32_e32 v159, v159
	v_add_f32_e32 v220, v158, v220
	s_waitcnt lgkmcnt(6)
	v_mfma_f32_32x32x16_bf16 v[50:65], v[194:197], v[146:149], v[50:65]
	v_exp_f32_e32 v160, v160
	v_add_f32_e32 v220, v159, v220
	v_exp_f32_e32 v161, v161
	v_add_f32_e32 v220, v160, v220
	v_cvt_pk_bf16_f32 v150, v154, v155
	s_waitcnt lgkmcnt(4)
	v_mfma_f32_32x32x16_bf16 v[34:49], v[198:201], v[146:149], v[34:49]
	v_add_f32_e32 v220, v161, v220
	v_cvt_pk_bf16_f32 v151, v156, v157
	v_cvt_pk_bf16_f32 v152, v158, v159
	v_cvt_pk_bf16_f32 v153, v160, v161
	v_add_f32_e32 v209, v209, v220
	ds_read_b64_tr_b16 v[154:155], v219 offset:17536
	ds_read_b64_tr_b16 v[156:157], v219 offset:20096
	ds_read_b64_tr_b16 v[158:159], v219 offset:17600
	ds_read_b64_tr_b16 v[160:161], v219 offset:20160
	s_waitcnt lgkmcnt(6)
	v_mfma_f32_32x32x16_bf16 v[114:129], v[202:205], v[150:153], v[114:129]
	v_exp_f32_e32 v130, v130
	v_exp_f32_e32 v131, v131
	v_exp_f32_e32 v132, v132
	v_add_f32_e32 v213, v130, v131
	v_exp_f32_e32 v133, v133
	s_waitcnt lgkmcnt(4)
	v_mfma_f32_32x32x16_bf16 v[82:97], v[214:217], v[150:153], v[82:97]
	v_add_f32_e32 v213, v132, v213
	v_exp_f32_e32 v134, v134
	v_add_f32_e32 v213, v133, v213
	v_exp_f32_e32 v135, v135
	v_add_f32_e32 v213, v134, v213
	s_waitcnt lgkmcnt(2)
	v_mfma_f32_32x32x16_bf16 v[50:65], v[154:157], v[150:153], v[50:65]
	v_exp_f32_e32 v136, v136
	v_add_f32_e32 v213, v135, v213
	v_exp_f32_e32 v137, v137
	v_add_f32_e32 v213, v136, v213
	v_cvt_pk_bf16_f32 v130, v130, v131
	s_waitcnt lgkmcnt(0)
	v_mfma_f32_32x32x16_bf16 v[34:49], v[158:161], v[150:153], v[34:49]
	v_add_f32_e32 v213, v137, v213
	v_cvt_pk_bf16_f32 v131, v132, v133
	v_cvt_pk_bf16_f32 v132, v134, v135
	v_cvt_pk_bf16_f32 v133, v136, v137
	s_nop 1
	v_mfma_f32_32x32x16_bf16 v[98:113], v[244:247], v[130:133], v[98:113]
	v_exp_f32_e32 v138, v138
	v_exp_f32_e32 v139, v139
	v_add_f32_e32 v213, v138, v213
	v_exp_f32_e32 v140, v140
	v_add_f32_e32 v213, v139, v213
	v_exp_f32_e32 v141, v141
	v_mfma_f32_32x32x16_bf16 v[66:81], v[248:251], v[130:133], v[66:81]
	v_add_f32_e32 v213, v140, v213
	v_exp_f32_e32 v142, v142
	v_add_f32_e32 v213, v141, v213
	v_exp_f32_e32 v143, v143
	v_add_f32_e32 v213, v142, v213
	v_mfma_f32_32x32x16_bf16 v[18:33], v[194:197], v[130:133], v[18:33]
	v_exp_f32_e32 v144, v144
	v_add_f32_e32 v213, v143, v213
	v_exp_f32_e32 v145, v145
	v_add_f32_e32 v213, v144, v213
	v_cvt_pk_bf16_f32 v134, v138, v139
	v_mfma_f32_32x32x16_bf16 v[2:17], v[198:201], v[130:133], v[2:17]
	v_add_f32_e32 v213, v145, v213
	v_cvt_pk_bf16_f32 v135, v140, v141
	v_cvt_pk_bf16_f32 v136, v142, v143
	v_cvt_pk_bf16_f32 v137, v144, v145
	v_add_f32_e32 v208, v208, v213
	s_nop 1
	v_mfma_f32_32x32x16_bf16 v[98:113], v[202:205], v[134:137], v[98:113]
	s_waitcnt vmcnt(2)
	v_add_u32_e32 v139, s2, v233
	ds_write_b128 v139, v[182:185]
	s_waitcnt vmcnt(1)
	v_add_u32_e32 v143, s2, v232
	ds_write_b128 v143, v[186:189] offset:17408
	v_mfma_f32_32x32x16_bf16 v[66:81], v[214:217], v[134:137], v[66:81]
	s_waitcnt vmcnt(0)
	v_add_u32_e32 v144, s2, v234
	ds_write_b128 v144, v[190:193] offset:17408
	v_mfma_f32_32x32x16_bf16 v[18:33], v[154:157], v[134:137], v[18:33]
	v_mfma_f32_32x32x16_bf16 v[2:17], v[158:161], v[134:137], v[2:17]
	s_branch .LBB0_495
